# WD0 transposes moved into ATT0 (items 192..783) so that barrier 7 (GU0 to D0) becomes row-block-group-local too; only barriers 1, 3, 4 remain grid-wide
# speedup vs baseline: 1.0414x; 1.0033x over previous
.LBB0_124:
	s_or_b64 exec, exec, s[4:5]
	s_waitcnt vmcnt(0)
	s_barrier
	s_mov_b64 s[4:5], exec
	v_readlane_b32 s0, v219, 25
	v_readlane_b32 s1, v219, 26
	s_and_b64 s[0:1], s[4:5], s[0:1]
	s_mov_b64 exec, s[0:1]
	s_cbranch_execz .LBB0_176
	v_readlane_b32 s0, v219, 27
	v_readlane_b32 s1, v219, 28
	v_readlane_b32 s2, v219, 30
	s_waitcnt vmcnt(0) lgkmcnt(0)
	buffer_inv sc1
	s_and_b32 s3, s2, 31
	s_lshl_b32 s3, s3, 7
	s_add_i32 s3, s3, 64
	v_mov_b32_e32 v1, s3
	v_mov_b32_e32 v0, 1
	s_nop 1
	global_atomic_add v1, v0, s[0:1]
	s_mov_b32 s15, 0
.Lgb2_spin:
	global_load_dword v2, v1, s[0:1] sc1
	s_waitcnt vmcnt(0)
	v_readfirstlane_b32 s13, v2
	s_nop 1
	s_cmp_ge_u32 s13, 8
	s_cbranch_scc1 .Lgb2_done
	s_sleep 1
	s_add_i32 s15, s15, 1
	s_cmp_lt_u32 s15, 0x200000
	s_cbranch_scc1 .Lgb2_spin

.LBB0_512:
	s_waitcnt vmcnt(0)
	s_waitcnt vmcnt(0) lgkmcnt(0)
	s_barrier
	s_mov_b64 s[4:5], exec
	v_readlane_b32 s0, v219, 25
	v_readlane_b32 s1, v219, 26
	s_and_b64 s[0:1], s[4:5], s[0:1]
	s_mov_b64 exec, s[0:1]
	s_cbranch_execz .LBB0_564
	v_readlane_b32 s0, v219, 27
	v_readlane_b32 s1, v219, 28
	v_readlane_b32 s2, v219, 30
	s_waitcnt vmcnt(0) lgkmcnt(0)
	buffer_inv sc1
	s_and_b32 s3, s2, 31
	s_lshl_b32 s3, s3, 7
	s_add_i32 s3, s3, 64
	v_mov_b32_e32 v1, s3
	v_mov_b32_e32 v0, 1
	s_nop 1
	global_atomic_add v1, v0, s[0:1]
	s_mov_b32 s15, 0
.Lgb5_spin:
	global_load_dword v2, v1, s[0:1] sc1
	s_waitcnt vmcnt(0)
	v_readfirstlane_b32 s13, v2
	s_nop 1
	s_cmp_ge_u32 s13, 16
	s_cbranch_scc1 .Lgb5_done
	s_sleep 1
	s_add_i32 s15, s15, 1
	s_cmp_lt_u32 s15, 0x200000
	s_cbranch_scc1 .Lgb5_spin

.LBB0_693:
	v_readlane_b32 s78, v219, 30
	s_nop 3
	s_cmpk_lt_u32 s78, 0x80
	s_cbranch_scc1 .Lgu0h_skip
	v_writelane_b32 v220, s0, 0
	v_writelane_b32 v220, s1, 1
	v_writelane_b32 v220, s2, 2
	v_writelane_b32 v220, s3, 3
	v_writelane_b32 v220, s4, 4
	v_writelane_b32 v220, s5, 5
	v_writelane_b32 v220, s6, 6
	v_writelane_b32 v220, s7, 7
	v_writelane_b32 v220, s8, 8
	v_writelane_b32 v220, s9, 9
	v_writelane_b32 v220, s10, 10
	v_writelane_b32 v220, s11, 11
	v_writelane_b32 v220, s12, 12
	v_writelane_b32 v220, s13, 13
	v_writelane_b32 v220, s14, 14
	v_writelane_b32 v220, s15, 15
	v_writelane_b32 v220, s16, 16
	v_writelane_b32 v220, s17, 17
	v_writelane_b32 v220, s18, 18
	v_writelane_b32 v220, s19, 19
	v_writelane_b32 v220, s20, 20
	v_writelane_b32 v220, s21, 21
	v_writelane_b32 v220, s22, 22
	v_writelane_b32 v220, s23, 23
	v_writelane_b32 v220, s24, 24
	v_writelane_b32 v220, s25, 25
	v_writelane_b32 v220, s26, 26
	v_writelane_b32 v220, s27, 27
	v_writelane_b32 v220, s36, 28
	v_writelane_b32 v220, s37, 29
	v_writelane_b32 v220, s38, 30
	v_writelane_b32 v220, s39, 31
	v_writelane_b32 v220, s40, 32
	v_writelane_b32 v220, s41, 33
	v_writelane_b32 v220, s42, 34
	v_writelane_b32 v220, s43, 35
	v_writelane_b32 v220, s44, 36
	v_writelane_b32 v220, s45, 37
	v_writelane_b32 v220, s46, 38
	v_writelane_b32 v220, s47, 39
	v_writelane_b32 v220, s48, 40
	v_writelane_b32 v220, s49, 41
	v_writelane_b32 v220, s50, 42
	v_writelane_b32 v220, s51, 43
	s_cmpk_gt_i32 s78, 0x17f
	s_waitcnt vmcnt(0) lgkmcnt(0)
	s_barrier
	s_cbranch_scc1 .Lgu0h_BB0_1034
	s_movk_i32 s1, 0x2100
	v_and_b32_e32 v4, 56, v144
	v_mad_u32_u24 v1, v148, s1, 0
	v_lshrrev_b32_e32 v0, 5, v149
	v_and_b32_e32 v2, 31, v168
	v_mul_u32_u24_e32 v3, 0x84, v4
	v_lshlrev_b32_e32 v7, 2, v185
	s_add_i32 s0, s78, 0x290
	v_mov_b32_e32 v5, 0
	v_lshl_add_u32 v6, v2, 2, v1
	s_movk_i32 s1, 0x84
	v_add3_u32 v20, v1, v3, v7
	v_or_b32_e32 v21, 8, v185
	v_or_b32_e32 v22, 16, v185
	v_or_b32_e32 v23, 24, v185
	v_mov_b32_e32 v1, v0
	s_movk_i32 s2, 0x187f
	v_mov_b32_e32 v24, 0xffffe780
	v_mov_b32_e32 v25, 0xc00
	v_mov_b32_e32 v26, 0x600
	s_movk_i32 s3, 0x1ff
	s_movk_i32 s4, 0xcff
	v_lshlrev_b32_e32 v8, 2, v2
	v_lshlrev_b32_e32 v10, 1, v4
	v_mov_b32_e32 v27, 0x2c0000
	v_mov_b32_e32 v28, 0x1400000
	v_mov_b32_e32 v29, 0x2980000
	v_mov_b32_e32 v30, 0x900000
	v_mov_b32_e32 v31, 0x1e80000
	v_mov_b32_e32 v32, 0x700000
	v_mov_b32_e32 v33, 0x1c80000
	v_mov_b32_e32 v34, 0x100000
	v_mov_b32_e32 v35, 0x1980000

.Lgu0h_BB0_1034:
	s_barrier
	v_readlane_b32 s0, v220, 0
	v_readlane_b32 s1, v220, 1
	v_readlane_b32 s2, v220, 2
	v_readlane_b32 s3, v220, 3
	v_readlane_b32 s4, v220, 4
	v_readlane_b32 s5, v220, 5
	v_readlane_b32 s6, v220, 6
	v_readlane_b32 s7, v220, 7
	v_readlane_b32 s8, v220, 8
	v_readlane_b32 s9, v220, 9
	v_readlane_b32 s10, v220, 10
	v_readlane_b32 s11, v220, 11
	v_readlane_b32 s12, v220, 12
	v_readlane_b32 s13, v220, 13
	v_readlane_b32 s14, v220, 14
	v_readlane_b32 s15, v220, 15
	v_readlane_b32 s16, v220, 16
	v_readlane_b32 s17, v220, 17
	v_readlane_b32 s18, v220, 18
	v_readlane_b32 s19, v220, 19
	v_readlane_b32 s20, v220, 20
	v_readlane_b32 s21, v220, 21
	v_readlane_b32 s22, v220, 22
	v_readlane_b32 s23, v220, 23
	v_readlane_b32 s24, v220, 24
	v_readlane_b32 s25, v220, 25
	v_readlane_b32 s26, v220, 26
	v_readlane_b32 s27, v220, 27
	v_readlane_b32 s36, v220, 28
	v_readlane_b32 s37, v220, 29
	v_readlane_b32 s38, v220, 30
	v_readlane_b32 s39, v220, 31
	v_readlane_b32 s40, v220, 32
	v_readlane_b32 s41, v220, 33
	v_readlane_b32 s42, v220, 34
	v_readlane_b32 s43, v220, 35
	v_readlane_b32 s44, v220, 36
	v_readlane_b32 s45, v220, 37
	v_readlane_b32 s46, v220, 38
	v_readlane_b32 s47, v220, 39
	v_readlane_b32 s48, v220, 40
	v_readlane_b32 s49, v220, 41
	v_readlane_b32 s50, v220, 42
	v_readlane_b32 s51, v220, 43
	s_nop 3
.Lgu0h_skip:
	s_waitcnt vmcnt(0)
	s_waitcnt vmcnt(0) lgkmcnt(0)
	s_barrier
	s_mov_b64 s[4:5], exec
	v_readlane_b32 s0, v219, 25
	v_readlane_b32 s1, v219, 26
	s_and_b64 s[0:1], s[4:5], s[0:1]
	s_mov_b64 exec, s[0:1]
	s_cbranch_execz .LBB0_745
	v_readlane_b32 s0, v219, 27
	v_readlane_b32 s1, v219, 28
	v_readlane_b32 s2, v219, 30
	s_waitcnt vmcnt(0) lgkmcnt(0)
	buffer_inv sc1
	s_and_b32 s3, s2, 31
	s_lshl_b32 s3, s3, 7
	s_add_i32 s3, s3, 64
	v_mov_b32_e32 v1, s3
	v_mov_b32_e32 v0, 1
	s_nop 1
	global_atomic_add v1, v0, s[0:1]
	s_mov_b32 s15, 0

.Lgb9_done:
	v_mov_b32_e32 v1, 0x1040
	s_mov_b32 s15, 0
.Lgb9_spin2:
	global_load_dword v2, v1, s[0:1] sc1
	s_waitcnt vmcnt(0)
	v_readfirstlane_b32 s13, v2
	s_nop 1
	s_cmp_ge_u32 s13, 256
	s_cbranch_scc1 .Lgb9_done2
	s_sleep 4
	s_add_i32 s15, s15, 1
	s_cmp_lt_u32 s15, 0x200000
	s_cbranch_scc1 .Lgb9_spin2

.Lgb13_done:
	v_mov_b32_e32 v1, 0x1140
	s_mov_b32 s15, 0

.Lgb14_spin:
	global_load_dword v2, v1, s[0:1] sc1
	s_waitcnt vmcnt(0)
	v_readfirstlane_b32 s13, v2
	s_nop 1
	s_cmp_ge_u32 s13, 72
	s_cbranch_scc1 .Lgb14_done
	s_sleep 1
	s_add_i32 s15, s15, 1
	s_cmp_lt_u32 s15, 0x200000
	s_cbranch_scc1 .Lgb14_spin

.Lgb15_spin:
	global_load_dword v2, v1, s[0:1] sc1
	s_waitcnt vmcnt(0)
	v_readfirstlane_b32 s13, v2
	s_nop 1
	s_cmp_ge_u32 s13, 80
	s_cbranch_scc1 .Lgb15_done
	s_sleep 1
	s_add_i32 s15, s15, 1
	s_cmp_lt_u32 s15, 0x200000
	s_cbranch_scc1 .Lgb15_spin
